# v27 + attention ping copy QK section fully restructured with one-step-ahead fragment reads (v25 idea) plus hoisted PV reads
# baseline (speedup 1.0000x reference)
; __device__ __forceinline__ void finishSM(f32x16& p0, f32x16& p1, float alpha, float& l_reg, bf16x8& pa0, bf16x8& pa1, bf16x8& pa2, bf16x8& pa3) {
; #pragma unroll
;     for (int r = 0; r < 16; ++r) p1[r] = __builtin_amdgcn_exp2f(p1[r]);
;     float ps = 0;
; #pragma unroll
;     for (int r = 0; r < 16; ++r) ps += p0[r];
; #pragma unroll
;     for (int r = 0; r < 16; ++r) ps += p1[r];
;     { auto rr = __builtin_amdgcn_permlane32_swap(__float_as_uint(ps), __float_as_uint(ps), false, false); ps = __uint_as_float(rr[0]) + __uint_as_float(rr[1]); }
;     l_reg = l_reg * alpha + ps;
;     ...
;     PK4(p0, 0, pa0); PK4(p0, 8, pa1); PK4(p1, 0, pa2); PK4(p1, 8, pa3);
;     ...
; }
; __device__ __forceinline__ void qkt(f32x16& p0, f32x16& p1, const char* Ks, const bf16x8* qr, const char* qrl, int r32, int hi) {
;     p0 = f32x16{}; p1 = f32x16{};
; #pragma unroll
;     for (int d0 = 0; d0 < 12; ++d0) { const int cb = (d0 * 16 + hi * 8) * 2;
;         const bf16x8 b0 = *reinterpret_cast<const bf16x8*>(Ks + KSWZ(r32, cb));
;         const bf16x8 b1 = *reinterpret_cast<const bf16x8*>(Ks + KSWZ(32 + r32, cb));
;         const bf16x8 qq = d0 < QREG ? qr[d0 < QREG ? d0 : 0] : *reinterpret_cast<const bf16x8*>(qrl + (d0 - QREG) * 1024);
;         p0 = __builtin_amdgcn_mfma_f32_32x32x16_bf16(b0, qq, p0, 0, 0, 0);
;         p1 = __builtin_amdgcn_mfma_f32_32x32x16_bf16(b1, qq, p1, 0, 0, 0); }
.LBB0_1380:
	v_add_u32_e32 v68, s14, v183
	ds_read_b128 v[64:67], v68
	ds_read_b128 v[68:71], v68 offset:16384
	v_add_u32_e32 v224, s14, v185
	ds_read_b128 v[220:223], v224
	ds_read_b128 v[224:227], v224 offset:16384
	v_add_f32_e32 v140, 0, v136
	s_waitcnt lgkmcnt(3)
	v_mfma_f32_32x32x16_bf16 v[80:95], v[64:67], v[116:119], 0
	v_add_f32_e32 v140, v166, v140
	v_add_f32_e32 v140, v137, v140
	v_add_f32_e32 v140, v167, v140
	v_add_f32_e32 v140, v138, v140
	v_add_f32_e32 v140, v168, v140
	v_add_f32_e32 v140, v139, v140
	v_add_f32_e32 v140, v165, v140
	s_waitcnt lgkmcnt(2)
	v_mfma_f32_32x32x16_bf16 v[64:79], v[68:71], v[116:119], 0
	v_add_f32_e32 v140, v144, v140
	v_add_f32_e32 v140, v146, v140
	v_add_f32_e32 v140, v145, v140
	v_add_f32_e32 v140, v164, v140
	v_exp_f32_e32 v132, v132
	v_add_f32_e32 v140, v141, v140
	v_exp_f32_e32 v133, v133
	v_add_u32_e32 v232, s14, v187
	ds_read_b128 v[228:231], v232
	ds_read_b128 v[232:235], v232 offset:16384
	s_waitcnt lgkmcnt(3)
	v_mfma_f32_32x32x16_bf16 v[80:95], v[220:223], v[112:115], v[80:95]
	v_add_f32_e32 v140, v143, v140
	v_exp_f32_e32 v134, v134
	v_add_f32_e32 v140, v142, v140
	v_exp_f32_e32 v135, v135
	v_add_f32_e32 v140, v147, v140
	s_waitcnt lgkmcnt(2)
	v_mfma_f32_32x32x16_bf16 v[64:79], v[224:227], v[112:115], v[64:79]
	v_exp_f32_e32 v122, v122
	v_add_f32_e32 v140, v132, v140
	v_exp_f32_e32 v123, v123
	v_add_f32_e32 v140, v133, v140
	v_exp_f32_e32 v124, v124
	v_add_f32_e32 v140, v134, v140
	v_add_u32_e32 v224, s14, v189
	ds_read_b128 v[220:223], v224
	ds_read_b128 v[224:227], v224 offset:16384
	s_waitcnt lgkmcnt(3)
	v_mfma_f32_32x32x16_bf16 v[80:95], v[228:231], v[108:111], v[80:95]
	v_exp_f32_e32 v125, v125
	v_add_f32_e32 v140, v135, v140
	v_exp_f32_e32 v126, v126
	v_add_f32_e32 v140, v122, v140
	v_exp_f32_e32 v127, v127
	v_add_f32_e32 v140, v123, v140
	v_exp_f32_e32 v130, v130
	s_waitcnt lgkmcnt(2)
	v_mfma_f32_32x32x16_bf16 v[64:79], v[232:235], v[108:111], v[64:79]
	v_add_f32_e32 v140, v124, v140
	v_exp_f32_e32 v131, v131
	v_add_f32_e32 v140, v125, v140
	v_exp_f32_e32 v120, v120
	v_add_f32_e32 v140, v126, v140
	v_exp_f32_e32 v121, v121
	v_add_u32_e32 v232, s14, v191
	ds_read_b128 v[228:231], v232
	ds_read_b128 v[232:235], v232 offset:16384
	s_waitcnt lgkmcnt(3)
	v_mfma_f32_32x32x16_bf16 v[80:95], v[220:223], v[104:107], v[80:95]
	v_add_f32_e32 v140, v127, v140
	v_exp_f32_e32 v128, v128
	v_add_f32_e32 v140, v130, v140
	v_exp_f32_e32 v129, v129
	v_add_f32_e32 v140, v131, v140
	s_waitcnt lgkmcnt(2)
	v_mfma_f32_32x32x16_bf16 v[64:79], v[224:227], v[104:107], v[64:79]
	v_add_f32_e32 v140, v120, v140
	v_add_f32_e32 v140, v121, v140
	v_add_f32_e32 v140, v128, v140
	v_add_u32_e32 v224, s14, v193
	ds_read_b128 v[220:223], v224
	ds_read_b128 v[224:227], v224 offset:16384
	s_waitcnt lgkmcnt(3)
	v_mfma_f32_32x32x16_bf16 v[80:95], v[228:231], v[100:103], v[80:95]
	s_waitcnt lgkmcnt(2)
	v_mfma_f32_32x32x16_bf16 v[64:79], v[232:235], v[100:103], v[64:79]
	ds_read_b128 v[240:243], v177
	v_add_u32_e32 v236, s14, v195
	ds_read_b128 v[232:235], v236
	ds_read_b128 v[236:239], v236 offset:16384
	s_waitcnt lgkmcnt(4)
	v_mfma_f32_32x32x16_bf16 v[80:95], v[220:223], v[96:99], v[80:95]
	s_waitcnt lgkmcnt(3)
	v_mfma_f32_32x32x16_bf16 v[64:79], v[224:227], v[96:99], v[64:79]
	ds_read_b128 v[228:231], v177 offset:1024
	v_add_u32_e32 v224, s14, v197
	ds_read_b128 v[220:223], v224
	ds_read_b128 v[224:227], v224 offset:16384
	s_waitcnt lgkmcnt(4)
	v_mfma_f32_32x32x16_bf16 v[80:95], v[232:235], v[240:243], v[80:95]
	s_waitcnt lgkmcnt(3)
	v_mfma_f32_32x32x16_bf16 v[64:79], v[236:239], v[240:243], v[64:79]
	ds_read_b128 v[240:243], v177 offset:2048
	v_add_u32_e32 v236, s14, v199
	ds_read_b128 v[232:235], v236
	ds_read_b128 v[236:239], v236 offset:16384
	s_waitcnt lgkmcnt(4)
	v_mfma_f32_32x32x16_bf16 v[80:95], v[220:223], v[228:231], v[80:95]
	s_waitcnt lgkmcnt(3)
	v_mfma_f32_32x32x16_bf16 v[64:79], v[224:227], v[228:231], v[64:79]
	ds_read_b128 v[228:231], v177 offset:3072
	v_add_u32_e32 v224, s14, v201
	ds_read_b128 v[220:223], v224
	ds_read_b128 v[224:227], v224 offset:16384
	s_waitcnt lgkmcnt(4)
	v_mfma_f32_32x32x16_bf16 v[80:95], v[232:235], v[240:243], v[80:95]
	s_waitcnt lgkmcnt(3)
	v_mfma_f32_32x32x16_bf16 v[64:79], v[236:239], v[240:243], v[64:79]
	ds_read_b128 v[240:243], v177 offset:4096
	v_add_u32_e32 v236, s14, v203
	ds_read_b128 v[232:235], v236
	ds_read_b128 v[236:239], v236 offset:16384
	s_waitcnt lgkmcnt(4)
	v_mfma_f32_32x32x16_bf16 v[80:95], v[220:223], v[228:231], v[80:95]
	s_waitcnt lgkmcnt(3)
	v_mfma_f32_32x32x16_bf16 v[64:79], v[224:227], v[228:231], v[64:79]
	ds_read_b128 v[228:231], v177 offset:5120
	v_add_u32_e32 v224, s14, v205
	ds_read_b128 v[220:223], v224
	ds_read_b128 v[224:227], v224 offset:16384
	s_waitcnt lgkmcnt(4)
	v_mfma_f32_32x32x16_bf16 v[80:95], v[232:235], v[240:243], v[80:95]
	s_waitcnt lgkmcnt(3)
	v_mfma_f32_32x32x16_bf16 v[64:79], v[236:239], v[240:243], v[64:79]
	v_cvt_pk_bf16_f32 v136, v136, v166
	v_cvt_pk_bf16_f32 v137, v137, v167
	v_cvt_pk_bf16_f32 v138, v138, v168
	v_cvt_pk_bf16_f32 v139, v139, v165
	v_cvt_pk_bf16_f32 v144, v144, v146
	v_cvt_pk_bf16_f32 v145, v145, v164
	s_waitcnt lgkmcnt(1)
	v_mfma_f32_32x32x16_bf16 v[80:95], v[220:223], v[228:231], v[80:95]
	v_add_f32_e32 v232, v129, v140
	v_mov_b32_e32 v233, v232
	v_cvt_pk_bf16_f32 v146, v141, v143
	v_cvt_pk_bf16_f32 v147, v142, v147
	v_cvt_pk_bf16_f32 v234, v132, v133
	v_cvt_pk_bf16_f32 v235, v134, v135
	s_nop 1
	v_permlane32_swap_b32_e32 v232, v233
	s_waitcnt lgkmcnt(0)
; __device__ __forceinline__ void finishSM(f32x16& p0, f32x16& p1, float alpha, float& l_reg, bf16x8& pa0, bf16x8& pa1, bf16x8& pa2, bf16x8& pa3) {
; #pragma unroll
;     for (int r = 0; r < 16; ++r) p1[r] = __builtin_amdgcn_exp2f(p1[r]);
;     float ps = 0;
; #pragma unroll
;     for (int r = 0; r < 16; ++r) ps += p0[r];
; #pragma unroll
;     for (int r = 0; r < 16; ++r) ps += p1[r];
;     { auto rr = __builtin_amdgcn_permlane32_swap(__float_as_uint(ps), __float_as_uint(ps), false, false); ps = __uint_as_float(rr[0]) + __uint_as_float(rr[1]); }
;     l_reg = l_reg * alpha + ps;
;     ...
;     PK4(p0, 0, pa0); PK4(p0, 8, pa1); PK4(p1, 0, pa2); PK4(p1, 8, pa3);
;     ...
; }
; __device__ __forceinline__ void qkt(f32x16& p0, f32x16& p1, const char* Ks, const bf16x8* qr, const char* qrl, int r32, int hi) {
;     p0 = f32x16{}; p1 = f32x16{};
; #pragma unroll
;     for (int d0 = 0; d0 < 12; ++d0) { const int cb = (d0 * 16 + hi * 8) * 2;
;         const bf16x8 b0 = *reinterpret_cast<const bf16x8*>(Ks + KSWZ(r32, cb));
;         const bf16x8 b1 = *reinterpret_cast<const bf16x8*>(Ks + KSWZ(32 + r32, cb));
;         const bf16x8 qq = d0 < QREG ? qr[d0 < QREG ? d0 : 0] : *reinterpret_cast<const bf16x8*>(qrl + (d0 - QREG) * 1024);
;         p0 = __builtin_amdgcn_mfma_f32_32x32x16_bf16(b0, qq, p0, 0, 0, 0);
;         p1 = __builtin_amdgcn_mfma_f32_32x32x16_bf16(b1, qq, p1, 0, 0, 0); }
; }
; __device__ __forceinline__ int v_st(int k, int c) { const int kk = (k & ~0xC) | ((k & 4) << 1) | ((k & 8) >> 1); return ((kk >> 3) * 4 + (c >> 5)) * 512 + ((kk & 7) * 32 + (c & 31)) * 2; }
; __device__ __forceinline__ int v_rd_base(int lane) { return ((lane & 3) << 3) | (((lane >> 2) & 3) << 6) | (((lane >> 4) & 1) << 5) | (((lane >> 5) & 1) << 8); }
; template <int OFF> __device__ __forceinline__ s16x4 tr_read(int vb) { s16x4 r; asm volatile("ds_read_b64_tr_b16 %0, %1 offset:%2" : "=&v"(r) : "v"(vb), "i"(OFF) : "memory"); return r; }
; template <int D0> __device__ __forceinline__ void pv_one(f32x16& od, int vb, bf16x8 pa0, bf16x8 pa1, bf16x8 pa2, bf16x8 pa3) {
;     const s16x4 l0 = tr_read<v_rd_off(D0, 0, 0)>(vb), h0 = tr_read<v_rd_off(D0, 0, 1)>(vb), l1 = tr_read<v_rd_off(D0, 1, 0)>(vb), h1 = tr_read<v_rd_off(D0, 1, 1)>(vb);
;     const s16x4 l2 = tr_read<v_rd_off(D0, 2, 0)>(vb), h2 = tr_read<v_rd_off(D0, 2, 1)>(vb), l3 = tr_read<v_rd_off(D0, 3, 0)>(vb), h3 = tr_read<v_rd_off(D0, 3, 1)>(vb);
	v_mfma_f32_32x32x16_bf16 v[64:79], v[224:227], v[228:231], v[64:79]
	ds_read_b64_tr_b16 v[242:243], v176 offset:0
	ds_read_b64_tr_b16 v[244:245], v176 offset:0x800
	ds_read_b64_tr_b16 v[246:247], v176 offset:0x1000
	ds_read_b64_tr_b16 v[248:249], v176 offset:0x1800
	ds_read_b64_tr_b16 v[250:251], v176 offset:0x2000
	ds_read_b64_tr_b16 v[252:253], v176 offset:0x2800
	ds_read_b64_tr_b16 v[208:209], v176 offset:0x3000
	ds_read_b64_tr_b16 v[210:211], v176 offset:0x3800
	v_cvt_pk_bf16_f32 v236, v122, v123
	v_permlane32_swap_b32_e32 v136, v138
	v_cvt_pk_bf16_f32 v237, v124, v125
	v_permlane32_swap_b32_e32 v234, v236
	v_cvt_pk_bf16_f32 v238, v126, v127
	v_cvt_pk_bf16_f32 v239, v130, v131
	v_cvt_pk_bf16_f32 v240, v120, v121
	v_cvt_pk_bf16_f32 v241, v128, v129
	v_permlane32_swap_b32_e32 v137, v139
	v_permlane32_swap_b32_e32 v144, v146
	v_permlane32_swap_b32_e32 v145, v147
	v_permlane32_swap_b32_e32 v235, v237
	v_permlane32_swap_b32_e32 v238, v240
	v_permlane32_swap_b32_e32 v239, v241
	v_lshl_add_u64 v[164:165], s[68:69], 0, v[156:157]
	s_mov_b32 s4, 0x23480000
	v_add_co_u32_e32 v120, vcc, s4, v164
	s_mov_b32 s4, 0x234a0000
	s_nop 0
	v_addc_co_u32_e32 v121, vcc, 0, v165, vcc
	v_add_co_u32_e32 v124, vcc, s4, v164
	v_lshl_add_u64 v[166:167], s[68:69], 0, v[154:155]
	s_nop 0
	v_addc_co_u32_e32 v125, vcc, 0, v165, vcc
	v_add_co_u32_e32 v128, vcc, s97, v166
	v_lshl_add_u64 v[168:169], s[68:69], 0, v[152:153]
	s_nop 0
	v_addc_co_u32_e32 v129, vcc, 0, v167, vcc
	v_add_co_u32_e32 v132, vcc, s97, v168
	v_lshl_add_u64 v[170:171], s[68:69], 0, v[150:151]
	s_nop 0
	v_addc_co_u32_e32 v133, vcc, 0, v169, vcc
	v_add_co_u32_e32 v140, vcc, s97, v170
	global_load_dwordx4 v[120:123], v[120:121], off
	s_nop 0
	global_load_dwordx4 v[124:127], v[124:125], off
	s_nop 0
	global_load_dwordx4 v[128:131], v[128:129], off
	s_nop 0
	global_load_dwordx4 v[132:135], v[132:133], off
	v_addc_co_u32_e32 v141, vcc, 0, v171, vcc
	global_load_dwordx4 v[140:143], v[140:141], off
	s_waitcnt lgkmcnt(0)
	s_nop 0
	v_mfma_f32_32x32x16_bf16 v[0:15], v[136:139], v[242:245], v[0:15]
	v_mfma_f32_32x32x16_bf16 v[0:15], v[144:147], v[246:249], v[0:15]
	v_mfma_f32_32x32x16_bf16 v[0:15], v[234:237], v[250:253], v[0:15]
	v_mfma_f32_32x32x16_bf16 v[0:15], v[238:241], v[208:211], v[0:15]
	ds_read_b64_tr_b16 v[208:209], v176 offset:0x200
	ds_read_b64_tr_b16 v[210:211], v176 offset:0xa00
	ds_read_b64_tr_b16 v[242:243], v176 offset:0x1200
	ds_read_b64_tr_b16 v[244:245], v176 offset:0x1a00
	ds_read_b64_tr_b16 v[246:247], v176 offset:0x2200
	ds_read_b64_tr_b16 v[248:249], v176 offset:0x2a00
	ds_read_b64_tr_b16 v[250:251], v176 offset:0x3200
	ds_read_b64_tr_b16 v[252:253], v176 offset:0x3a00
	s_waitcnt lgkmcnt(0)
	s_nop 0
	v_mfma_f32_32x32x16_bf16 v[48:63], v[136:139], v[208:211], v[48:63]
	ds_read_b64_tr_b16 v[208:209], v176 offset:0x400
	ds_read_b64_tr_b16 v[210:211], v176 offset:0xc00
	v_mfma_f32_32x32x16_bf16 v[48:63], v[144:147], v[242:245], v[48:63]
	ds_read_b64_tr_b16 v[242:243], v176 offset:0x1400
	ds_read_b64_tr_b16 v[244:245], v176 offset:0x1c00
	v_mfma_f32_32x32x16_bf16 v[48:63], v[234:237], v[246:249], v[48:63]
	ds_read_b64_tr_b16 v[246:247], v176 offset:0x2400
	ds_read_b64_tr_b16 v[248:249], v176 offset:0x2c00
	v_mfma_f32_32x32x16_bf16 v[48:63], v[238:241], v[250:253], v[48:63]
	ds_read_b64_tr_b16 v[250:251], v176 offset:0x3400
	ds_read_b64_tr_b16 v[252:253], v176 offset:0x3c00
	s_waitcnt lgkmcnt(0)
	v_mfma_f32_32x32x16_bf16 v[32:47], v[136:139], v[208:211], v[32:47]
	ds_read_b64_tr_b16 v[208:209], v176 offset:0x600
	ds_read_b64_tr_b16 v[210:211], v176 offset:0xe00
	v_mfma_f32_32x32x16_bf16 v[32:47], v[144:147], v[242:245], v[32:47]
	ds_read_b64_tr_b16 v[242:243], v176 offset:0x1600
	ds_read_b64_tr_b16 v[244:245], v176 offset:0x1e00
	v_mfma_f32_32x32x16_bf16 v[32:47], v[234:237], v[246:249], v[32:47]
	ds_read_b64_tr_b16 v[246:247], v176 offset:0x2600
	ds_read_b64_tr_b16 v[248:249], v176 offset:0x2e00
	v_mfma_f32_32x32x16_bf16 v[32:47], v[238:241], v[250:253], v[32:47]
	ds_read_b64_tr_b16 v[250:251], v176 offset:0x3600
	ds_read_b64_tr_b16 v[252:253], v176 offset:0x3e00
	s_waitcnt lgkmcnt(0)
	v_mfma_f32_32x32x16_bf16 v[16:31], v[136:139], v[208:211], v[16:31]
	v_max_f32_e32 v136, v81, v81
	v_max_f32_e32 v137, v80, v80
	v_max_f32_e32 v136, v137, v136
	v_max3_f32 v136, v136, v82, v83
	v_max3_f32 v136, v136, v84, v85
	v_max3_f32 v136, v136, v86, v87
	v_max3_f32 v136, v136, v88, v89
	v_max3_f32 v136, v136, v90, v91
	v_mfma_f32_32x32x16_bf16 v[16:31], v[144:147], v[242:245], v[16:31]
	v_max3_f32 v136, v136, v92, v93
	v_max3_f32 v136, v136, v94, v95
	v_max3_f32 v136, v136, v64, v65
	v_max3_f32 v136, v136, v66, v67
	v_max3_f32 v136, v136, v68, v69
	v_max3_f32 v136, v136, v70, v71
	v_max3_f32 v136, v136, v72, v73
	v_max3_f32 v136, v136, v74, v75
	v_mfma_f32_32x32x16_bf16 v[16:31], v[234:237], v[246:249], v[16:31]
	v_max3_f32 v136, v136, v76, v77
	v_max3_f32 v136, v136, v78, v79
	v_mov_b32_e32 v137, v136
	s_nop 1
	v_permlane32_swap_b32_e32 v136, v137
	v_max_f32_e32 v137, v137, v137
	v_max_f32_e32 v136, v136, v136
	v_max_f32_e32 v136, v136, v137
	v_sub_f32_e32 v137, v136, v158
	v_cmp_ge_f32_e32 vcc, s62, v137
	v_max_f32_e32 v137, v158, v158
	v_mfma_f32_32x32x16_bf16 v[16:31], v[238:241], v[250:253], v[16:31]
	v_max_f32_e32 v136, v137, v136
	v_sub_f32_e32 v137, v158, v136
	v_exp_f32_e32 v137, v137
	s_cmp_eq_u64 vcc, exec
	s_cselect_b64 s[4:5], -1, 0
	s_barrier
; #define SWRITE(b) do { *(bf16x8*)(V_lds + (b) * SHM_V + vst0) = vs0; *(bf16x8*)(V_lds + (b) * SHM_V + vst1) = vs1; \
;     *(bf16x8*)(K_lds + (b) * SHM_K + KSWZ(kr0, kc0 * 16)) = ks0; *(bf16x8*)(K_lds + (b) * SHM_K + KSWZ(kr1, kc1 * 16)) = ks1; *(bf16x8*)(K_lds + (b) * SHM_K + KSWZ(kr2, kc2 * 16)) = ks2; } while (0)
; #define SWAIT() asm volatile("s_waitcnt vmcnt(0)" ::: "memory")
; #define RESC(a) do { if (__any((a) < 1.f)) { if (hi == 0) al_l[r32] = (a); asm volatile("s_waitcnt lgkmcnt(0)" ::: "memory"); \
;     _Pragma("unroll") for (int d = 0; d < 4; ++d) _Pragma("unroll") for (int r = 0; r < 16; ++r) o[d][r] *= al_l[crow(r, hi)]; } } while (0)
; __device__ __forceinline__ void attn_unit(const bf16_t* __restrict__ Qb, const bf16_t* __restrict__ Kh, const bf16_t* __restrict__ Vh, bf16_t* __restrict__ Ob, int seq, char* lds) {
;     ...
;         __syncthreads(); SWAIT(); SWRITE(1);
;         RESC(alA); __syncthreads();
	s_waitcnt vmcnt(0)
	v_cndmask_b32_e64 v234, v137, 1.0, s[4:5]
	v_cmp_gt_f32_e32 vcc, 1.0, v234
	s_waitcnt vmcnt(4)
	ds_write_b128 v178, v[120:123]
	s_waitcnt vmcnt(3)
	ds_write_b128 v179, v[124:127]
	s_waitcnt vmcnt(2)
	ds_write_b128 v180, v[128:131] offset:32768
	s_waitcnt vmcnt(1)
	ds_write_b128 v181, v[132:135] offset:32768
	s_waitcnt vmcnt(0)
	ds_write_b128 v182, v[140:143] offset:32768
	s_cbranch_vccz .LBB0_1384
	s_and_saveexec_b64 s[12:13], s[2:3]
	ds_write_b32 v173, v234 offset:128
	s_or_b64 exec, exec, s[12:13]
	s_waitcnt lgkmcnt(0)
	v_add_u32_e32 v132, v149, v160
	ds_read_b128 v[120:123], v132 offset:224
	ds_read_b128 v[124:127], v132 offset:192
	ds_read_b128 v[128:131], v132 offset:160
	ds_read_b128 v[132:135], v132 offset:128
	s_waitcnt lgkmcnt(3)
	v_pk_mul_f32 v[12:13], v[12:13], v[120:121]
	s_waitcnt lgkmcnt(2)
	v_pk_mul_f32 v[8:9], v[8:9], v[124:125]
	s_waitcnt lgkmcnt(1)
	v_pk_mul_f32 v[4:5], v[4:5], v[128:129]
	v_pk_mul_f32 v[14:15], v[14:15], v[122:123]
	v_pk_mul_f32 v[10:11], v[10:11], v[126:127]
	v_pk_mul_f32 v[6:7], v[6:7], v[130:131]
	s_waitcnt lgkmcnt(0)
	v_pk_mul_f32 v[2:3], v[2:3], v[134:135]
	v_pk_mul_f32 v[0:1], v[0:1], v[132:133]
	v_pk_mul_f32 v[60:61], v[60:61], v[120:121]
	v_pk_mul_f32 v[56:57], v[56:57], v[124:125]
	v_pk_mul_f32 v[52:53], v[52:53], v[128:129]
	v_pk_mul_f32 v[62:63], v[62:63], v[122:123]
	v_pk_mul_f32 v[58:59], v[58:59], v[126:127]
	v_pk_mul_f32 v[54:55], v[54:55], v[130:131]
	v_pk_mul_f32 v[50:51], v[50:51], v[134:135]
	v_pk_mul_f32 v[48:49], v[48:49], v[132:133]
	v_pk_mul_f32 v[44:45], v[44:45], v[120:121]
	v_pk_mul_f32 v[40:41], v[40:41], v[124:125]
	v_pk_mul_f32 v[36:37], v[36:37], v[128:129]
	v_pk_mul_f32 v[46:47], v[46:47], v[122:123]
	v_pk_mul_f32 v[42:43], v[42:43], v[126:127]
	v_pk_mul_f32 v[38:39], v[38:39], v[130:131]
	v_pk_mul_f32 v[34:35], v[34:35], v[134:135]
	v_pk_mul_f32 v[32:33], v[32:33], v[132:133]
	v_pk_mul_f32 v[28:29], v[28:29], v[120:121]
	v_pk_mul_f32 v[24:25], v[24:25], v[124:125]
	v_pk_mul_f32 v[20:21], v[20:21], v[128:129]
	v_pk_mul_f32 v[30:31], v[30:31], v[122:123]
	v_pk_mul_f32 v[26:27], v[26:27], v[126:127]
	v_pk_mul_f32 v[22:23], v[22:23], v[130:131]
	v_pk_mul_f32 v[18:19], v[18:19], v[134:135]
	v_pk_mul_f32 v[16:17], v[16:17], v[132:133]
